# bundle plus attention V fragments for the post-barrier PV MFMAs reloaded four gaps earlier (counted waits 4,4,4,8,10,2)
# baseline (speedup 1.0000x reference)
; template <int VAR> ...
;     ...
;     ka[0] = kp[0]; kb[0] = kp[1]; ka[1] = kp[2]; kb[1] = kp[3]; if (dk) glds16(gk, lk); SBAR();
;     { const f32x16 z = f32x16{};
;       QKM(x0, ka[0], qr[0], z);  SUM4(y0, 0); PKA(y0, 0);       SBAR();
;       QKM(x1, kb[0], qr[0], z);  SUM4(y0, 4); PKB(y0, 4, pa0);  KRD(2); if (dv) glds16(gv, lv); SBAR(); }
;     QKM(x0, ka[1], qr[1], x0); SUM4(y0, 8); PKA(y0, 8);       SBAR();
;     QKM(x1, kb[1], qr[1], x1); SUM4(y0, 12); PKB(y0, 12, pa1); KRD(3); if (dv) glds16(gv + 8192, lv + 8192); SBAR();
;     QKM(x0, ka[2], qr[2], x0); SUM4(y1, 0); PKA(y1, 0);       SBAR();
;     QKM(x1, kb[2], qr[2], x1); SUM4(y1, 4); PKB(y1, 4, pa2);  SBAR();
;     QKM(x0, ka[3], qr[3], x0); SUM4(y1, 8); PKA(y1, 8);       SBAR();
;     QKM(x1, kb[3], qr[3], x1); SUM4(y1, 12); PKB(y1, 12, pa3); VRD(0); VRD(1); SBAR();
;     VRD(2); VRD(3); SBAR();
;     if (near) {
;         float tA[4], uA[4], tB[4], uB[4];
;     ...
;         TLD(tA, uA, 0); SBAR(); TLD(tB, uB, 1); SBAR();
;         asm volatile("s_nop 15\n\ts_nop 7" : "+v"(x0), "+v"(x1));
;         TAD(tA, uA, 0); SBAR(); TLD(tA, uA, 2); SBAR(); TAD(tB, uB, 1); SBAR(); TLD(tB, uB, 3); SBAR(); TAD(tA, uA, 2); SBAR(); TAD(tB, uB, 3);
;     ...
;     } else if (__builtin_expect(shift != 0.f, 0)) {
;         asm volatile("s_nop 15\n\ts_nop 7" : "+v"(x0), "+v"(x1));
; #pragma unroll
;         for (int r = 0; r < 16; ++r) { asm volatile("v_sub_f32 %0, %0, %1" : "+v"(x0[r]) : "v"(shift)); asm volatile("v_sub_f32 %0, %0, %1" : "+v"(x1[r]) : "v"(shift)); }
;     }
;     SBAR();
;     ...
;     GAPB(0, pa0); GAPB(1, pa1); GAPB(2, pa2); GAPB(3, pa3); GAPB(4, pa0); GAPB(5, pa1); GAPB(6, pa2); GAPB(7, pa3);
;     GAPB(8, pa0); GAPB(9, pa1); GAPB(10, pa2); GAPB(11, pa3);
;     if (wv == 3) asm volatile("s_waitcnt vmcnt(3)" ::: "memory"); else if (wv == 2) asm volatile("s_waitcnt vmcnt(2)" ::: "memory"); else asm volatile("s_waitcnt vmcnt(0)" ::: "memory");
;     asm volatile("s_waitcnt lgkmcnt(0)\n\ts_barrier" ::: "memory");
;     if (pre) { const char* a0_ = Kn + (((0 + hi) ^ sw) << 4); const char* a1_ = Kn + (((2 + hi) ^ sw) << 4);
;         kp[0] = *reinterpret_cast<const bf16x8*>(a0_); kp[1] = *reinterpret_cast<const bf16x8*>(a0_ + 32 * 128); kp[2] = *reinterpret_cast<const bf16x8*>(a1_); kp[3] = *reinterpret_cast<const bf16x8*>(a1_ + 32 * 128); }
;     SBAR();
;     GAPB(12, pa0); GAPB(13, pa1); GAPB(14, pa2); GAPB(15, pa3);
.LBB0_367_u0:
	s_waitcnt lgkmcnt(4)
	v_mfma_f32_32x32x16_bf16 v[66:81], v[4:7], v[174:177], v[66:81]
	v_exp_f32_e32 v130, v130
	v_exp_f32_e32 v114, v114
	ds_read_b64_tr_b16 v[98:99], v214 offset:512
	ds_read_b64_tr_b16 v[100:101], v214 offset:768
	v_mfma_f32_32x32x16_bf16 v[66:81], v[8:11], v[170:173], v[66:81]
	v_exp_f32_e32 v131, v131
	v_exp_f32_e32 v115, v115
	ds_read_b64_tr_b16 v[102:103], v214 offset:4608
	ds_read_b64_tr_b16 v[104:105], v214 offset:4864
	s_waitcnt lgkmcnt(4)
	v_mfma_f32_32x32x16_bf16 v[66:81], v[12:15], v[166:169], v[66:81]
	v_exp_f32_e32 v132, v132
	v_exp_f32_e32 v116, v116
	ds_read_b64_tr_b16 v[106:107], v214 offset:8704
	ds_read_b64_tr_b16 v[108:109], v214 offset:8960
	v_mfma_f32_32x32x16_bf16 v[66:81], v[178:181], v[162:165], v[66:81]
	v_exp_f32_e32 v133, v133
	v_exp_f32_e32 v117, v117
	ds_read_b64_tr_b16 v[110:111], v214 offset:12800
	ds_read_b64_tr_b16 v[112:113], v214 offset:13056
	s_waitcnt lgkmcnt(4)
	v_mfma_f32_32x32x16_bf16 v[50:65], v[4:7], v[98:101], v[50:65]
	v_exp_f32_e32 v134, v134
	v_exp_f32_e32 v118, v118
	v_exp_f32_e32 v142, v142
	ds_read_b64_tr_b16 v[82:83], v214 offset:1024
	ds_read_b64_tr_b16 v[84:85], v214 offset:1280
	ds_read_b64_tr_b16 v[98:99], v214 offset:1536
	ds_read_b64_tr_b16 v[100:101], v214 offset:1792
	v_mfma_f32_32x32x16_bf16 v[50:65], v[8:11], v[102:105], v[50:65]
	v_exp_f32_e32 v135, v135
	v_exp_f32_e32 v119, v119
	v_exp_f32_e32 v126, v126
	ds_read_b64_tr_b16 v[86:87], v214 offset:5120
	ds_read_b64_tr_b16 v[88:89], v214 offset:5376
	ds_read_b64_tr_b16 v[102:103], v214 offset:5632
	ds_read_b64_tr_b16 v[104:105], v214 offset:5888
	s_waitcnt lgkmcnt(8)
	v_mfma_f32_32x32x16_bf16 v[50:65], v[12:15], v[106:109], v[50:65]
	v_exp_f32_e32 v136, v136
	v_exp_f32_e32 v120, v120
	v_exp_f32_e32 v143, v143
	ds_read_b64_tr_b16 v[90:91], v214 offset:9216
	ds_read_b64_tr_b16 v[92:93], v214 offset:9472
	ds_read_b64_tr_b16 v[106:107], v214 offset:9728
	ds_read_b64_tr_b16 v[108:109], v214 offset:9984
	v_mfma_f32_32x32x16_bf16 v[50:65], v[178:181], v[110:113], v[50:65]
	v_exp_f32_e32 v137, v137
	v_exp_f32_e32 v121, v121
	v_exp_f32_e32 v127, v127
	ds_read_b64_tr_b16 v[94:95], v214 offset:13312
	ds_read_b64_tr_b16 v[96:97], v214 offset:13568
	ds_read_b64_tr_b16 v[110:111], v214 offset:13824
	ds_read_b64_tr_b16 v[112:113], v214 offset:14080
	s_waitcnt lgkmcnt(10)
	v_mfma_f32_32x32x16_bf16 v[34:49], v[4:7], v[82:85], v[34:49]
	v_exp_f32_e32 v138, v138
	v_exp_f32_e32 v122, v122
	v_exp_f32_e32 v144, v144
	v_mfma_f32_32x32x16_bf16 v[34:49], v[8:11], v[86:89], v[34:49]
	v_exp_f32_e32 v139, v139
	v_exp_f32_e32 v123, v123
	v_exp_f32_e32 v128, v128
	s_waitcnt lgkmcnt(2)
	v_mfma_f32_32x32x16_bf16 v[34:49], v[12:15], v[90:93], v[34:49]
	v_exp_f32_e32 v140, v140
	v_exp_f32_e32 v124, v124
	v_exp_f32_e32 v145, v145
	v_mfma_f32_32x32x16_bf16 v[34:49], v[178:181], v[94:97], v[34:49]
	v_exp_f32_e32 v141, v141
	v_exp_f32_e32 v125, v125
	v_exp_f32_e32 v129, v129
	s_waitcnt vmcnt(3) lgkmcnt(0)
	s_barrier
	ds_read_b128 v[174:177], v237 offset:49152
	ds_read_b128 v[170:173], v237 offset:53248
	ds_read_b128 v[166:169], v238 offset:49152
	ds_read_b128 v[162:165], v238 offset:53248
	v_mfma_f32_32x32x16_bf16 v[18:33], v[4:7], v[98:101], v[18:33]
	v_mfma_f32_32x32x16_bf16 v[18:33], v[8:11], v[102:105], v[18:33]
	v_mfma_f32_32x32x16_bf16 v[18:33], v[12:15], v[106:109], v[18:33]
	v_mfma_f32_32x32x16_bf16 v[18:33], v[178:181], v[110:113], v[18:33]
	s_add_i32 s20, s20, 2
	s_add_i32 m0, s88, 0x2000
	s_mov_b32 s69, s87
	global_load_lds_dwordx4 v241, s[0:1]
	s_waitcnt lgkmcnt(2)
	v_mfma_f32_32x32x16_bf16 v[82:97], v[174:177], v[146:149], 0
	v_add_f32_e32 v4, v130, v131
	v_add_f32_e32 v5, v132, v133
	v_add_f32_e32 v6, v4, v5
	v_cvt_pk_bf16_f32 v4, v130, v131
	v_cvt_pk_bf16_f32 v5, v132, v133
	v_add_f32_e32 v7, v134, v135
	v_add_f32_e32 v8, v136, v137
	v_mfma_f32_32x32x16_bf16 v[98:113], v[170:173], v[146:149], 0
	v_add_f32_e32 v7, v7, v8
	v_add_f32_e32 v8, v7, v6
	v_cvt_pk_bf16_f32 v6, v134, v135
	v_cvt_pk_bf16_f32 v7, v136, v137
	s_mov_b32 m0, s69
	ds_read_b128 v[14:17], v239 offset:49152
	ds_read_b128 v[130:133], v239 offset:53248
	global_load_lds_dwordx4 v242, s[90:91]
	s_waitcnt lgkmcnt(2)
	v_mfma_f32_32x32x16_bf16 v[82:97], v[166:169], v[150:153], v[82:97]
	v_add_f32_e32 v9, v138, v139
	v_add_f32_e32 v10, v140, v141
	v_add_f32_e32 v9, v9, v10
	v_add_f32_e32 v10, v9, v8
	v_cvt_pk_bf16_f32 v8, v138, v139
	v_cvt_pk_bf16_f32 v9, v140, v141
	v_add_f32_e32 v11, v142, v143
	v_add_f32_e32 v134, v144, v145
	v_mfma_f32_32x32x16_bf16 v[98:113], v[162:165], v[150:153], v[98:113]
	v_add_f32_e32 v11, v11, v134
	v_add_f32_e32 v178, v11, v10
	v_cvt_pk_bf16_f32 v10, v142, v143
	v_cvt_pk_bf16_f32 v11, v144, v145
	ds_read_b128 v[138:141], v240 offset:49152
	ds_read_b128 v[134:137], v240 offset:53248
	s_add_i32 m0, s69, 0x2000
	s_cmp_le_i32 s89, s100
	global_load_lds_dwordx4 v243, s[90:91]
	s_waitcnt lgkmcnt(2)
	v_mfma_f32_32x32x16_bf16 v[82:97], v[14:17], v[154:157], v[82:97]
	v_add_f32_e32 v12, v114, v115
	v_add_f32_e32 v13, v116, v117
	v_add_f32_e32 v12, v12, v13
	v_add_f32_e32 v142, v12, v178
	v_cvt_pk_bf16_f32 v12, v114, v115
	v_cvt_pk_bf16_f32 v13, v116, v117
	v_mfma_f32_32x32x16_bf16 v[98:113], v[130:133], v[154:157], v[98:113]
	v_add_f32_e32 v14, v118, v119
	v_add_f32_e32 v15, v120, v121
	v_add_f32_e32 v14, v14, v15
	v_add_f32_e32 v16, v14, v142
	v_cvt_pk_bf16_f32 v14, v118, v119
	v_cvt_pk_bf16_f32 v15, v120, v121
	s_waitcnt lgkmcnt(0)
	v_mfma_f32_32x32x16_bf16 v[82:97], v[138:141], v[158:161], v[82:97]
	v_add_f32_e32 v17, v122, v123
	v_add_f32_e32 v130, v124, v125
	v_add_f32_e32 v17, v17, v130
	v_add_f32_e32 v16, v17, v16
	v_cvt_pk_bf16_f32 v178, v122, v123
	v_cvt_pk_bf16_f32 v179, v124, v125
	v_add_f32_e32 v17, v126, v127
	v_add_f32_e32 v130, v128, v129
	v_add_f32_e32 v17, v17, v130
	v_add_f32_e32 v16, v17, v16
	v_cvt_pk_bf16_f32 v180, v126, v127
	v_cvt_pk_bf16_f32 v181, v128, v129
	v_mfma_f32_32x32x16_bf16 v[98:113], v[134:137], v[158:161], v[98:113]
	ds_read_b64_tr_b16 v[194:195], v214 offset:16384
	ds_read_b64_tr_b16 v[196:197], v214 offset:16640
	ds_read_b64_tr_b16 v[190:191], v214 offset:20480
	ds_read_b64_tr_b16 v[192:193], v214 offset:20736
	ds_read_b64_tr_b16 v[186:187], v214 offset:24576
	ds_read_b64_tr_b16 v[188:189], v214 offset:24832
	ds_read_b64_tr_b16 v[182:183], v214 offset:28672
	ds_read_b64_tr_b16 v[184:185], v214 offset:28928
	s_cbranch_scc0 .Lp2s_disp2_u0
; template <int VAR> ...
;     ...
;     GAPB(0, pa0); GAPB(1, pa1); GAPB(2, pa2); GAPB(3, pa3); GAPB(4, pa0); GAPB(5, pa1); GAPB(6, pa2); GAPB(7, pa3);
;     GAPB(8, pa0); GAPB(9, pa1); GAPB(10, pa2); GAPB(11, pa3);
;     if (wv == 3) asm volatile("s_waitcnt vmcnt(3)" ::: "memory"); else if (wv == 2) asm volatile("s_waitcnt vmcnt(2)" ::: "memory"); else asm volatile("s_waitcnt vmcnt(0)" ::: "memory");
;     asm volatile("s_waitcnt lgkmcnt(0)\n\ts_barrier" ::: "memory");
;     if (pre) { const char* a0_ = Kn + (((0 + hi) ^ sw) << 4); const char* a1_ = Kn + (((2 + hi) ^ sw) << 4);
;         kp[0] = *reinterpret_cast<const bf16x8*>(a0_); kp[1] = *reinterpret_cast<const bf16x8*>(a0_ + 32 * 128); kp[2] = *reinterpret_cast<const bf16x8*>(a1_); kp[3] = *reinterpret_cast<const bf16x8*>(a1_ + 32 * 128); }
.LBB0_385_u0:
	s_waitcnt lgkmcnt(4)
	v_mfma_f32_32x32x16_bf16 v[66:81], v[4:7], v[194:197], v[66:81]
	v_exp_f32_e32 v82, v82
	v_exp_f32_e32 v98, v98
	ds_read_b64_tr_b16 v[114:115], v214 offset:16896
	ds_read_b64_tr_b16 v[116:117], v214 offset:17152
	v_mfma_f32_32x32x16_bf16 v[66:81], v[8:11], v[190:193], v[66:81]
	v_exp_f32_e32 v83, v83
	v_exp_f32_e32 v99, v99
	ds_read_b64_tr_b16 v[118:119], v214 offset:20992
	ds_read_b64_tr_b16 v[120:121], v214 offset:21248
	s_waitcnt lgkmcnt(4)
	v_mfma_f32_32x32x16_bf16 v[66:81], v[12:15], v[186:189], v[66:81]
	v_exp_f32_e32 v84, v84
	v_exp_f32_e32 v100, v100
	ds_read_b64_tr_b16 v[122:123], v214 offset:25088
	ds_read_b64_tr_b16 v[124:125], v214 offset:25344
	v_mfma_f32_32x32x16_bf16 v[66:81], v[178:181], v[182:185], v[66:81]
	v_exp_f32_e32 v85, v85
	v_exp_f32_e32 v101, v101
	ds_read_b64_tr_b16 v[126:127], v214 offset:29184
	ds_read_b64_tr_b16 v[128:129], v214 offset:29440
	s_waitcnt lgkmcnt(4)
	v_mfma_f32_32x32x16_bf16 v[50:65], v[4:7], v[114:117], v[50:65]
	v_exp_f32_e32 v86, v86
	v_exp_f32_e32 v102, v102
	v_exp_f32_e32 v94, v94
	ds_read_b64_tr_b16 v[130:131], v214 offset:17408
	ds_read_b64_tr_b16 v[132:133], v214 offset:17664
	ds_read_b64_tr_b16 v[114:115], v214 offset:17920
	ds_read_b64_tr_b16 v[116:117], v214 offset:18176
	v_mfma_f32_32x32x16_bf16 v[50:65], v[8:11], v[118:121], v[50:65]
	v_exp_f32_e32 v87, v87
	v_exp_f32_e32 v103, v103
	v_exp_f32_e32 v110, v110
	ds_read_b64_tr_b16 v[134:135], v214 offset:21504
	ds_read_b64_tr_b16 v[136:137], v214 offset:21760
	ds_read_b64_tr_b16 v[118:119], v214 offset:22016
	ds_read_b64_tr_b16 v[120:121], v214 offset:22272
	s_waitcnt lgkmcnt(8)
	v_mfma_f32_32x32x16_bf16 v[50:65], v[12:15], v[122:125], v[50:65]
	v_exp_f32_e32 v88, v88
	v_exp_f32_e32 v104, v104
	v_exp_f32_e32 v95, v95
	ds_read_b64_tr_b16 v[138:139], v214 offset:25600
	ds_read_b64_tr_b16 v[140:141], v214 offset:25856
	ds_read_b64_tr_b16 v[122:123], v214 offset:26112
	ds_read_b64_tr_b16 v[124:125], v214 offset:26368
	v_mfma_f32_32x32x16_bf16 v[50:65], v[178:181], v[126:129], v[50:65]
	v_exp_f32_e32 v89, v89
	v_exp_f32_e32 v105, v105
	v_exp_f32_e32 v111, v111
	ds_read_b64_tr_b16 v[142:143], v214 offset:29696
	ds_read_b64_tr_b16 v[144:145], v214 offset:29952
	ds_read_b64_tr_b16 v[126:127], v214 offset:30208
	ds_read_b64_tr_b16 v[128:129], v214 offset:30464
	s_waitcnt lgkmcnt(10)
	v_mfma_f32_32x32x16_bf16 v[34:49], v[4:7], v[130:133], v[34:49]
	v_exp_f32_e32 v90, v90
	v_exp_f32_e32 v106, v106
	v_exp_f32_e32 v96, v96
	v_mfma_f32_32x32x16_bf16 v[34:49], v[8:11], v[134:137], v[34:49]
	v_exp_f32_e32 v91, v91
	v_exp_f32_e32 v107, v107
	v_exp_f32_e32 v112, v112
	s_waitcnt lgkmcnt(2)
	v_mfma_f32_32x32x16_bf16 v[34:49], v[12:15], v[138:141], v[34:49]
	v_exp_f32_e32 v92, v92
	v_exp_f32_e32 v108, v108
	v_exp_f32_e32 v97, v97
	v_mfma_f32_32x32x16_bf16 v[34:49], v[178:181], v[142:145], v[34:49]
	v_exp_f32_e32 v93, v93
	v_exp_f32_e32 v109, v109
	v_exp_f32_e32 v113, v113
	s_waitcnt vmcnt(3) lgkmcnt(0)
	s_barrier
	s_cmp_gt_i32 s62, s60
	s_cbranch_scc1 .LBB0_394_u0
	ds_read_b128 v[174:177], v237 offset:32768
	ds_read_b128 v[170:173], v237 offset:36864
	ds_read_b128 v[166:169], v238 offset:32768
	ds_read_b128 v[162:165], v238 offset:36864

; template <int VAR> ...
;     ...
;     ka[0] = kp[0]; kb[0] = kp[1]; ka[1] = kp[2]; kb[1] = kp[3]; if (dk) glds16(gk, lk); SBAR();
;     { const f32x16 z = f32x16{};
;       QKM(x0, ka[0], qr[0], z);  SUM4(y0, 0); PKA(y0, 0);       SBAR();
;       QKM(x1, kb[0], qr[0], z);  SUM4(y0, 4); PKB(y0, 4, pa0);  KRD(2); if (dv) glds16(gv, lv); SBAR(); }
;     QKM(x0, ka[1], qr[1], x0); SUM4(y0, 8); PKA(y0, 8);       SBAR();
;     QKM(x1, kb[1], qr[1], x1); SUM4(y0, 12); PKB(y0, 12, pa1); KRD(3); if (dv) glds16(gv + 8192, lv + 8192); SBAR();
;     QKM(x0, ka[2], qr[2], x0); SUM4(y1, 0); PKA(y1, 0);       SBAR();
;     QKM(x1, kb[2], qr[2], x1); SUM4(y1, 4); PKB(y1, 4, pa2);  SBAR();
;     QKM(x0, ka[3], qr[3], x0); SUM4(y1, 8); PKA(y1, 8);       SBAR();
;     QKM(x1, kb[3], qr[3], x1); SUM4(y1, 12); PKB(y1, 12, pa3); VRD(0); VRD(1); SBAR();
;     VRD(2); VRD(3); SBAR();
;     if (near) {
;         float tA[4], uA[4], tB[4], uB[4];
;     ...
;         TLD(tA, uA, 0); SBAR(); TLD(tB, uB, 1); SBAR();
;         asm volatile("s_nop 15\n\ts_nop 7" : "+v"(x0), "+v"(x1));
;         TAD(tA, uA, 0); SBAR(); TLD(tA, uA, 2); SBAR(); TAD(tB, uB, 1); SBAR(); TLD(tB, uB, 3); SBAR(); TAD(tA, uA, 2); SBAR(); TAD(tB, uB, 3);
;     ...
;     } else if (__builtin_expect(shift != 0.f, 0)) {
;         asm volatile("s_nop 15\n\ts_nop 7" : "+v"(x0), "+v"(x1));
; #pragma unroll
;         for (int r = 0; r < 16; ++r) { asm volatile("v_sub_f32 %0, %0, %1" : "+v"(x0[r]) : "v"(shift)); asm volatile("v_sub_f32 %0, %0, %1" : "+v"(x1[r]) : "v"(shift)); }
;     }
;     SBAR();
;     ...
;     GAPB(0, pa0); GAPB(1, pa1); GAPB(2, pa2); GAPB(3, pa3); GAPB(4, pa0); GAPB(5, pa1); GAPB(6, pa2); GAPB(7, pa3);
;     GAPB(8, pa0); GAPB(9, pa1); GAPB(10, pa2); GAPB(11, pa3);
;     if (wv == 3) asm volatile("s_waitcnt vmcnt(3)" ::: "memory"); else if (wv == 2) asm volatile("s_waitcnt vmcnt(2)" ::: "memory"); else asm volatile("s_waitcnt vmcnt(0)" ::: "memory");
;     asm volatile("s_waitcnt lgkmcnt(0)\n\ts_barrier" ::: "memory");
;     if (pre) { const char* a0_ = Kn + (((0 + hi) ^ sw) << 4); const char* a1_ = Kn + (((2 + hi) ^ sw) << 4);
;         kp[0] = *reinterpret_cast<const bf16x8*>(a0_); kp[1] = *reinterpret_cast<const bf16x8*>(a0_ + 32 * 128); kp[2] = *reinterpret_cast<const bf16x8*>(a1_); kp[3] = *reinterpret_cast<const bf16x8*>(a1_ + 32 * 128); }
;     SBAR();
;     GAPB(12, pa0); GAPB(13, pa1); GAPB(14, pa2); GAPB(15, pa3);
.LBB0_367_u1:
	s_waitcnt lgkmcnt(4)
	v_mfma_f32_32x32x16_bf16 v[66:81], v[4:7], v[174:177], v[66:81]
	v_exp_f32_e32 v130, v130
	v_exp_f32_e32 v114, v114
	ds_read_b64_tr_b16 v[98:99], v214 offset:33280
	ds_read_b64_tr_b16 v[100:101], v214 offset:33536
	v_mfma_f32_32x32x16_bf16 v[66:81], v[8:11], v[170:173], v[66:81]
	v_exp_f32_e32 v131, v131
	v_exp_f32_e32 v115, v115
	ds_read_b64_tr_b16 v[102:103], v214 offset:37376
	ds_read_b64_tr_b16 v[104:105], v214 offset:37632
	s_waitcnt lgkmcnt(4)
	v_mfma_f32_32x32x16_bf16 v[66:81], v[12:15], v[166:169], v[66:81]
	v_exp_f32_e32 v132, v132
	v_exp_f32_e32 v116, v116
	ds_read_b64_tr_b16 v[106:107], v214 offset:41472
	ds_read_b64_tr_b16 v[108:109], v214 offset:41728
	v_mfma_f32_32x32x16_bf16 v[66:81], v[178:181], v[162:165], v[66:81]
	v_exp_f32_e32 v133, v133
	v_exp_f32_e32 v117, v117
	ds_read_b64_tr_b16 v[110:111], v214 offset:45568
	ds_read_b64_tr_b16 v[112:113], v214 offset:45824
	s_waitcnt lgkmcnt(4)
	v_mfma_f32_32x32x16_bf16 v[50:65], v[4:7], v[98:101], v[50:65]
	v_exp_f32_e32 v134, v134
	v_exp_f32_e32 v118, v118
	v_exp_f32_e32 v142, v142
	ds_read_b64_tr_b16 v[82:83], v214 offset:33792
	ds_read_b64_tr_b16 v[84:85], v214 offset:34048
	ds_read_b64_tr_b16 v[98:99], v214 offset:34304
	ds_read_b64_tr_b16 v[100:101], v214 offset:34560
	v_mfma_f32_32x32x16_bf16 v[50:65], v[8:11], v[102:105], v[50:65]
	v_exp_f32_e32 v135, v135
	v_exp_f32_e32 v119, v119
	v_exp_f32_e32 v126, v126
	ds_read_b64_tr_b16 v[86:87], v214 offset:37888
	ds_read_b64_tr_b16 v[88:89], v214 offset:38144
	ds_read_b64_tr_b16 v[102:103], v214 offset:38400
	ds_read_b64_tr_b16 v[104:105], v214 offset:38656
	s_waitcnt lgkmcnt(8)
	v_mfma_f32_32x32x16_bf16 v[50:65], v[12:15], v[106:109], v[50:65]
	v_exp_f32_e32 v136, v136
	v_exp_f32_e32 v120, v120
	v_exp_f32_e32 v143, v143
	ds_read_b64_tr_b16 v[90:91], v214 offset:41984
	ds_read_b64_tr_b16 v[92:93], v214 offset:42240
	ds_read_b64_tr_b16 v[106:107], v214 offset:42496
	ds_read_b64_tr_b16 v[108:109], v214 offset:42752
	v_mfma_f32_32x32x16_bf16 v[50:65], v[178:181], v[110:113], v[50:65]
	v_exp_f32_e32 v137, v137
	v_exp_f32_e32 v121, v121
	v_exp_f32_e32 v127, v127
	ds_read_b64_tr_b16 v[94:95], v214 offset:46080
	ds_read_b64_tr_b16 v[96:97], v214 offset:46336
	ds_read_b64_tr_b16 v[110:111], v214 offset:46592
	ds_read_b64_tr_b16 v[112:113], v214 offset:46848
	s_waitcnt lgkmcnt(10)
	v_mfma_f32_32x32x16_bf16 v[34:49], v[4:7], v[82:85], v[34:49]
	v_exp_f32_e32 v138, v138
	v_exp_f32_e32 v122, v122
	v_exp_f32_e32 v144, v144
	v_mfma_f32_32x32x16_bf16 v[34:49], v[8:11], v[86:89], v[34:49]
	v_exp_f32_e32 v139, v139
	v_exp_f32_e32 v123, v123
	v_exp_f32_e32 v128, v128
	s_waitcnt lgkmcnt(2)
	v_mfma_f32_32x32x16_bf16 v[34:49], v[12:15], v[90:93], v[34:49]
	v_exp_f32_e32 v140, v140
	v_exp_f32_e32 v124, v124
	v_exp_f32_e32 v145, v145
	v_mfma_f32_32x32x16_bf16 v[34:49], v[178:181], v[94:97], v[34:49]
	v_exp_f32_e32 v141, v141
	v_exp_f32_e32 v125, v125
	v_exp_f32_e32 v129, v129
	s_waitcnt vmcnt(3) lgkmcnt(0)
	s_barrier
	ds_read_b128 v[174:177], v237 offset:40960
	ds_read_b128 v[170:173], v237 offset:45056
	ds_read_b128 v[166:169], v238 offset:40960
	ds_read_b128 v[162:165], v238 offset:45056
	v_mfma_f32_32x32x16_bf16 v[18:33], v[4:7], v[98:101], v[18:33]
	v_mfma_f32_32x32x16_bf16 v[18:33], v[8:11], v[102:105], v[18:33]
	v_mfma_f32_32x32x16_bf16 v[18:33], v[12:15], v[106:109], v[18:33]
	v_mfma_f32_32x32x16_bf16 v[18:33], v[178:181], v[110:113], v[18:33]
	s_add_i32 s20, s20, 2
	s_mov_b32 m0, s88
	s_add_i32 s69, s87, 0x8000
	global_load_lds_dwordx4 v241, s[0:1]
	s_waitcnt lgkmcnt(2)
	v_mfma_f32_32x32x16_bf16 v[82:97], v[174:177], v[146:149], 0
	v_add_f32_e32 v4, v130, v131
	v_add_f32_e32 v5, v132, v133
	v_add_f32_e32 v6, v4, v5
	v_cvt_pk_bf16_f32 v4, v130, v131
	v_cvt_pk_bf16_f32 v5, v132, v133
	v_add_f32_e32 v7, v134, v135
	v_add_f32_e32 v8, v136, v137
	v_mfma_f32_32x32x16_bf16 v[98:113], v[170:173], v[146:149], 0
	v_add_f32_e32 v7, v7, v8
	v_add_f32_e32 v8, v7, v6
	v_cvt_pk_bf16_f32 v6, v134, v135
	v_cvt_pk_bf16_f32 v7, v136, v137
	s_mov_b32 m0, s69
	ds_read_b128 v[14:17], v239 offset:40960
	ds_read_b128 v[130:133], v239 offset:45056
	global_load_lds_dwordx4 v242, s[90:91]
	s_waitcnt lgkmcnt(2)
	v_mfma_f32_32x32x16_bf16 v[82:97], v[166:169], v[150:153], v[82:97]
	v_add_f32_e32 v9, v138, v139
	v_add_f32_e32 v10, v140, v141
	v_add_f32_e32 v9, v9, v10
	v_add_f32_e32 v10, v9, v8
	v_cvt_pk_bf16_f32 v8, v138, v139
	v_cvt_pk_bf16_f32 v9, v140, v141
	v_add_f32_e32 v11, v142, v143
	v_add_f32_e32 v134, v144, v145
	v_mfma_f32_32x32x16_bf16 v[98:113], v[162:165], v[150:153], v[98:113]
	v_add_f32_e32 v11, v11, v134
	v_add_f32_e32 v178, v11, v10
	v_cvt_pk_bf16_f32 v10, v142, v143
	v_cvt_pk_bf16_f32 v11, v144, v145
	ds_read_b128 v[138:141], v240 offset:40960
	ds_read_b128 v[134:137], v240 offset:45056
	s_add_i32 m0, s69, 0x2000
	s_cmp_le_i32 s89, s100
	global_load_lds_dwordx4 v243, s[90:91]
	s_waitcnt lgkmcnt(2)
	v_mfma_f32_32x32x16_bf16 v[82:97], v[14:17], v[154:157], v[82:97]
	v_add_f32_e32 v12, v114, v115
	v_add_f32_e32 v13, v116, v117
	v_add_f32_e32 v12, v12, v13
	v_add_f32_e32 v142, v12, v178
	v_cvt_pk_bf16_f32 v12, v114, v115
	v_cvt_pk_bf16_f32 v13, v116, v117
	v_mfma_f32_32x32x16_bf16 v[98:113], v[130:133], v[154:157], v[98:113]
	v_add_f32_e32 v14, v118, v119
	v_add_f32_e32 v15, v120, v121
	v_add_f32_e32 v14, v14, v15
	v_add_f32_e32 v16, v14, v142
	v_cvt_pk_bf16_f32 v14, v118, v119
	v_cvt_pk_bf16_f32 v15, v120, v121
	s_waitcnt lgkmcnt(0)
	v_mfma_f32_32x32x16_bf16 v[82:97], v[138:141], v[158:161], v[82:97]
	v_add_f32_e32 v17, v122, v123
	v_add_f32_e32 v130, v124, v125
	v_add_f32_e32 v17, v17, v130
	v_add_f32_e32 v16, v17, v16
	v_cvt_pk_bf16_f32 v178, v122, v123
	v_cvt_pk_bf16_f32 v179, v124, v125
	v_add_f32_e32 v17, v126, v127
	v_add_f32_e32 v130, v128, v129
	v_add_f32_e32 v17, v17, v130
	v_add_f32_e32 v16, v17, v16
	v_cvt_pk_bf16_f32 v180, v126, v127
	v_cvt_pk_bf16_f32 v181, v128, v129
	v_mfma_f32_32x32x16_bf16 v[98:113], v[134:137], v[158:161], v[98:113]
	ds_read_b64_tr_b16 v[194:195], v214 offset:0
	ds_read_b64_tr_b16 v[196:197], v214 offset:256
	ds_read_b64_tr_b16 v[190:191], v214 offset:4096
	ds_read_b64_tr_b16 v[192:193], v214 offset:4352
	ds_read_b64_tr_b16 v[186:187], v214 offset:8192
	ds_read_b64_tr_b16 v[188:189], v214 offset:8448
	ds_read_b64_tr_b16 v[182:183], v214 offset:12288
	ds_read_b64_tr_b16 v[184:185], v214 offset:12544
	s_cbranch_scc0 .Lp2s_disp2_u1
; template <int VAR> ...
;     ...
;     GAPB(0, pa0); GAPB(1, pa1); GAPB(2, pa2); GAPB(3, pa3); GAPB(4, pa0); GAPB(5, pa1); GAPB(6, pa2); GAPB(7, pa3);
;     GAPB(8, pa0); GAPB(9, pa1); GAPB(10, pa2); GAPB(11, pa3);
;     if (wv == 3) asm volatile("s_waitcnt vmcnt(3)" ::: "memory"); else if (wv == 2) asm volatile("s_waitcnt vmcnt(2)" ::: "memory"); else asm volatile("s_waitcnt vmcnt(0)" ::: "memory");
;     asm volatile("s_waitcnt lgkmcnt(0)\n\ts_barrier" ::: "memory");
;     if (pre) { const char* a0_ = Kn + (((0 + hi) ^ sw) << 4); const char* a1_ = Kn + (((2 + hi) ^ sw) << 4);
;         kp[0] = *reinterpret_cast<const bf16x8*>(a0_); kp[1] = *reinterpret_cast<const bf16x8*>(a0_ + 32 * 128); kp[2] = *reinterpret_cast<const bf16x8*>(a1_); kp[3] = *reinterpret_cast<const bf16x8*>(a1_ + 32 * 128); }
.LBB0_385_u1:
	s_waitcnt lgkmcnt(4)
	v_mfma_f32_32x32x16_bf16 v[66:81], v[4:7], v[194:197], v[66:81]
	v_exp_f32_e32 v82, v82
	v_exp_f32_e32 v98, v98
	ds_read_b64_tr_b16 v[114:115], v214 offset:512
	ds_read_b64_tr_b16 v[116:117], v214 offset:768
	v_mfma_f32_32x32x16_bf16 v[66:81], v[8:11], v[190:193], v[66:81]
	v_exp_f32_e32 v83, v83
	v_exp_f32_e32 v99, v99
	ds_read_b64_tr_b16 v[118:119], v214 offset:4608
	ds_read_b64_tr_b16 v[120:121], v214 offset:4864
	s_waitcnt lgkmcnt(4)
	v_mfma_f32_32x32x16_bf16 v[66:81], v[12:15], v[186:189], v[66:81]
	v_exp_f32_e32 v84, v84
	v_exp_f32_e32 v100, v100
	ds_read_b64_tr_b16 v[122:123], v214 offset:8704
	ds_read_b64_tr_b16 v[124:125], v214 offset:8960
	v_mfma_f32_32x32x16_bf16 v[66:81], v[178:181], v[182:185], v[66:81]
	v_exp_f32_e32 v85, v85
	v_exp_f32_e32 v101, v101
	ds_read_b64_tr_b16 v[126:127], v214 offset:12800
	ds_read_b64_tr_b16 v[128:129], v214 offset:13056
	s_waitcnt lgkmcnt(4)
	v_mfma_f32_32x32x16_bf16 v[50:65], v[4:7], v[114:117], v[50:65]
	v_exp_f32_e32 v86, v86
	v_exp_f32_e32 v102, v102
	v_exp_f32_e32 v94, v94
	ds_read_b64_tr_b16 v[130:131], v214 offset:1024
	ds_read_b64_tr_b16 v[132:133], v214 offset:1280
	ds_read_b64_tr_b16 v[114:115], v214 offset:1536
	ds_read_b64_tr_b16 v[116:117], v214 offset:1792
	v_mfma_f32_32x32x16_bf16 v[50:65], v[8:11], v[118:121], v[50:65]
	v_exp_f32_e32 v87, v87
	v_exp_f32_e32 v103, v103
	v_exp_f32_e32 v110, v110
	ds_read_b64_tr_b16 v[134:135], v214 offset:5120
	ds_read_b64_tr_b16 v[136:137], v214 offset:5376
	ds_read_b64_tr_b16 v[118:119], v214 offset:5632
	ds_read_b64_tr_b16 v[120:121], v214 offset:5888
	s_waitcnt lgkmcnt(8)
	v_mfma_f32_32x32x16_bf16 v[50:65], v[12:15], v[122:125], v[50:65]
	v_exp_f32_e32 v88, v88
	v_exp_f32_e32 v104, v104
	v_exp_f32_e32 v95, v95
	ds_read_b64_tr_b16 v[138:139], v214 offset:9216
	ds_read_b64_tr_b16 v[140:141], v214 offset:9472
	ds_read_b64_tr_b16 v[122:123], v214 offset:9728
	ds_read_b64_tr_b16 v[124:125], v214 offset:9984
	v_mfma_f32_32x32x16_bf16 v[50:65], v[178:181], v[126:129], v[50:65]
	v_exp_f32_e32 v89, v89
	v_exp_f32_e32 v105, v105
	v_exp_f32_e32 v111, v111
	ds_read_b64_tr_b16 v[142:143], v214 offset:13312
	ds_read_b64_tr_b16 v[144:145], v214 offset:13568
	ds_read_b64_tr_b16 v[126:127], v214 offset:13824
	ds_read_b64_tr_b16 v[128:129], v214 offset:14080
	s_waitcnt lgkmcnt(10)
	v_mfma_f32_32x32x16_bf16 v[34:49], v[4:7], v[130:133], v[34:49]
	v_exp_f32_e32 v90, v90
	v_exp_f32_e32 v106, v106
	v_exp_f32_e32 v96, v96
	v_mfma_f32_32x32x16_bf16 v[34:49], v[8:11], v[134:137], v[34:49]
	v_exp_f32_e32 v91, v91
	v_exp_f32_e32 v107, v107
	v_exp_f32_e32 v112, v112
	s_waitcnt lgkmcnt(2)
	v_mfma_f32_32x32x16_bf16 v[34:49], v[12:15], v[138:141], v[34:49]
	v_exp_f32_e32 v92, v92
	v_exp_f32_e32 v108, v108
	v_exp_f32_e32 v97, v97
	v_mfma_f32_32x32x16_bf16 v[34:49], v[178:181], v[142:145], v[34:49]
	v_exp_f32_e32 v93, v93
	v_exp_f32_e32 v109, v109
	v_exp_f32_e32 v113, v113
	s_waitcnt vmcnt(3) lgkmcnt(0)
	s_barrier
	s_cmp_gt_i32 s62, s60
	s_cbranch_scc1 .LBB0_394_u1
	ds_read_b128 v[174:177], v237 offset:49152
	ds_read_b128 v[170:173], v237 offset:53248
	ds_read_b128 v[166:169], v238 offset:49152
	ds_read_b128 v[162:165], v238 offset:53248

; template <int VAR> ...
;     ...
;     ka[0] = kp[0]; kb[0] = kp[1]; ka[1] = kp[2]; kb[1] = kp[3]; if (dk) glds16(gk, lk); SBAR();
;     { const f32x16 z = f32x16{};
;       QKM(x0, ka[0], qr[0], z);  SUM4(y0, 0); PKA(y0, 0);       SBAR();
;       QKM(x1, kb[0], qr[0], z);  SUM4(y0, 4); PKB(y0, 4, pa0);  KRD(2); if (dv) glds16(gv, lv); SBAR(); }
;     QKM(x0, ka[1], qr[1], x0); SUM4(y0, 8); PKA(y0, 8);       SBAR();
;     QKM(x1, kb[1], qr[1], x1); SUM4(y0, 12); PKB(y0, 12, pa1); KRD(3); if (dv) glds16(gv + 8192, lv + 8192); SBAR();
;     QKM(x0, ka[2], qr[2], x0); SUM4(y1, 0); PKA(y1, 0);       SBAR();
;     QKM(x1, kb[2], qr[2], x1); SUM4(y1, 4); PKB(y1, 4, pa2);  SBAR();
;     QKM(x0, ka[3], qr[3], x0); SUM4(y1, 8); PKA(y1, 8);       SBAR();
;     QKM(x1, kb[3], qr[3], x1); SUM4(y1, 12); PKB(y1, 12, pa3); VRD(0); VRD(1); SBAR();
;     VRD(2); VRD(3); SBAR();
;     if (near) {
;         float tA[4], uA[4], tB[4], uB[4];
;     ...
;         TLD(tA, uA, 0); SBAR(); TLD(tB, uB, 1); SBAR();
;         asm volatile("s_nop 15\n\ts_nop 7" : "+v"(x0), "+v"(x1));
;         TAD(tA, uA, 0); SBAR(); TLD(tA, uA, 2); SBAR(); TAD(tB, uB, 1); SBAR(); TLD(tB, uB, 3); SBAR(); TAD(tA, uA, 2); SBAR(); TAD(tB, uB, 3);
;     ...
;     } else if (__builtin_expect(shift != 0.f, 0)) {
;         asm volatile("s_nop 15\n\ts_nop 7" : "+v"(x0), "+v"(x1));
; #pragma unroll
;         for (int r = 0; r < 16; ++r) { asm volatile("v_sub_f32 %0, %0, %1" : "+v"(x0[r]) : "v"(shift)); asm volatile("v_sub_f32 %0, %0, %1" : "+v"(x1[r]) : "v"(shift)); }
;     }
;     SBAR();
;     ...
;     GAPB(0, pa0); GAPB(1, pa1); GAPB(2, pa2); GAPB(3, pa3); GAPB(4, pa0); GAPB(5, pa1); GAPB(6, pa2); GAPB(7, pa3);
;     GAPB(8, pa0); GAPB(9, pa1); GAPB(10, pa2); GAPB(11, pa3);
;     if (wv == 3) asm volatile("s_waitcnt vmcnt(3)" ::: "memory"); else if (wv == 2) asm volatile("s_waitcnt vmcnt(2)" ::: "memory"); else asm volatile("s_waitcnt vmcnt(0)" ::: "memory");
;     asm volatile("s_waitcnt lgkmcnt(0)\n\ts_barrier" ::: "memory");
;     if (pre) { const char* a0_ = Kn + (((0 + hi) ^ sw) << 4); const char* a1_ = Kn + (((2 + hi) ^ sw) << 4);
;         kp[0] = *reinterpret_cast<const bf16x8*>(a0_); kp[1] = *reinterpret_cast<const bf16x8*>(a0_ + 32 * 128); kp[2] = *reinterpret_cast<const bf16x8*>(a1_); kp[3] = *reinterpret_cast<const bf16x8*>(a1_ + 32 * 128); }
;     SBAR();
;     GAPB(12, pa0); GAPB(13, pa1); GAPB(14, pa2); GAPB(15, pa3);
.LBB0_367_u2:
	s_waitcnt lgkmcnt(4)
	v_mfma_f32_32x32x16_bf16 v[66:81], v[4:7], v[174:177], v[66:81]
	v_exp_f32_e32 v130, v130
	v_exp_f32_e32 v114, v114
	ds_read_b64_tr_b16 v[98:99], v214 offset:16896
	ds_read_b64_tr_b16 v[100:101], v214 offset:17152
	v_mfma_f32_32x32x16_bf16 v[66:81], v[8:11], v[170:173], v[66:81]
	v_exp_f32_e32 v131, v131
	v_exp_f32_e32 v115, v115
	ds_read_b64_tr_b16 v[102:103], v214 offset:20992
	ds_read_b64_tr_b16 v[104:105], v214 offset:21248
	s_waitcnt lgkmcnt(4)
	v_mfma_f32_32x32x16_bf16 v[66:81], v[12:15], v[166:169], v[66:81]
	v_exp_f32_e32 v132, v132
	v_exp_f32_e32 v116, v116
	ds_read_b64_tr_b16 v[106:107], v214 offset:25088
	ds_read_b64_tr_b16 v[108:109], v214 offset:25344
	v_mfma_f32_32x32x16_bf16 v[66:81], v[178:181], v[162:165], v[66:81]
	v_exp_f32_e32 v133, v133
	v_exp_f32_e32 v117, v117
	ds_read_b64_tr_b16 v[110:111], v214 offset:29184
	ds_read_b64_tr_b16 v[112:113], v214 offset:29440
	s_waitcnt lgkmcnt(4)
	v_mfma_f32_32x32x16_bf16 v[50:65], v[4:7], v[98:101], v[50:65]
	v_exp_f32_e32 v134, v134
	v_exp_f32_e32 v118, v118
	v_exp_f32_e32 v142, v142
	ds_read_b64_tr_b16 v[82:83], v214 offset:17408
	ds_read_b64_tr_b16 v[84:85], v214 offset:17664
	ds_read_b64_tr_b16 v[98:99], v214 offset:17920
	ds_read_b64_tr_b16 v[100:101], v214 offset:18176
	v_mfma_f32_32x32x16_bf16 v[50:65], v[8:11], v[102:105], v[50:65]
	v_exp_f32_e32 v135, v135
	v_exp_f32_e32 v119, v119
	v_exp_f32_e32 v126, v126
	ds_read_b64_tr_b16 v[86:87], v214 offset:21504
	ds_read_b64_tr_b16 v[88:89], v214 offset:21760
	ds_read_b64_tr_b16 v[102:103], v214 offset:22016
	ds_read_b64_tr_b16 v[104:105], v214 offset:22272
	s_waitcnt lgkmcnt(8)
	v_mfma_f32_32x32x16_bf16 v[50:65], v[12:15], v[106:109], v[50:65]
	v_exp_f32_e32 v136, v136
	v_exp_f32_e32 v120, v120
	v_exp_f32_e32 v143, v143
	ds_read_b64_tr_b16 v[90:91], v214 offset:25600
	ds_read_b64_tr_b16 v[92:93], v214 offset:25856
	ds_read_b64_tr_b16 v[106:107], v214 offset:26112
	ds_read_b64_tr_b16 v[108:109], v214 offset:26368
	v_mfma_f32_32x32x16_bf16 v[50:65], v[178:181], v[110:113], v[50:65]
	v_exp_f32_e32 v137, v137
	v_exp_f32_e32 v121, v121
	v_exp_f32_e32 v127, v127
	ds_read_b64_tr_b16 v[94:95], v214 offset:29696
	ds_read_b64_tr_b16 v[96:97], v214 offset:29952
	ds_read_b64_tr_b16 v[110:111], v214 offset:30208
	ds_read_b64_tr_b16 v[112:113], v214 offset:30464
	s_waitcnt lgkmcnt(10)
	v_mfma_f32_32x32x16_bf16 v[34:49], v[4:7], v[82:85], v[34:49]
	v_exp_f32_e32 v138, v138
	v_exp_f32_e32 v122, v122
	v_exp_f32_e32 v144, v144
	v_mfma_f32_32x32x16_bf16 v[34:49], v[8:11], v[86:89], v[34:49]
	v_exp_f32_e32 v139, v139
	v_exp_f32_e32 v123, v123
	v_exp_f32_e32 v128, v128
	s_waitcnt lgkmcnt(2)
	v_mfma_f32_32x32x16_bf16 v[34:49], v[12:15], v[90:93], v[34:49]
	v_exp_f32_e32 v140, v140
	v_exp_f32_e32 v124, v124
	v_exp_f32_e32 v145, v145
	v_mfma_f32_32x32x16_bf16 v[34:49], v[178:181], v[94:97], v[34:49]
	v_exp_f32_e32 v141, v141
	v_exp_f32_e32 v125, v125
	v_exp_f32_e32 v129, v129
	s_waitcnt vmcnt(3) lgkmcnt(0)
	s_barrier
	ds_read_b128 v[174:177], v237 offset:32768
	ds_read_b128 v[170:173], v237 offset:36864
	ds_read_b128 v[166:169], v238 offset:32768
	ds_read_b128 v[162:165], v238 offset:36864
	v_mfma_f32_32x32x16_bf16 v[18:33], v[4:7], v[98:101], v[18:33]
	v_mfma_f32_32x32x16_bf16 v[18:33], v[8:11], v[102:105], v[18:33]
	v_mfma_f32_32x32x16_bf16 v[18:33], v[12:15], v[106:109], v[18:33]
	v_mfma_f32_32x32x16_bf16 v[18:33], v[178:181], v[110:113], v[18:33]
	s_add_i32 s20, s20, 2
	s_add_i32 m0, s88, 0x4000
	s_add_i32 s69, s87, 0x4000
	global_load_lds_dwordx4 v241, s[0:1]
	s_waitcnt lgkmcnt(2)
	v_mfma_f32_32x32x16_bf16 v[82:97], v[174:177], v[146:149], 0
	v_add_f32_e32 v4, v130, v131
	v_add_f32_e32 v5, v132, v133
	v_add_f32_e32 v6, v4, v5
	v_cvt_pk_bf16_f32 v4, v130, v131
	v_cvt_pk_bf16_f32 v5, v132, v133
	v_add_f32_e32 v7, v134, v135
	v_add_f32_e32 v8, v136, v137
	v_mfma_f32_32x32x16_bf16 v[98:113], v[170:173], v[146:149], 0
	v_add_f32_e32 v7, v7, v8
	v_add_f32_e32 v8, v7, v6
	v_cvt_pk_bf16_f32 v6, v134, v135
	v_cvt_pk_bf16_f32 v7, v136, v137
	s_mov_b32 m0, s69
	ds_read_b128 v[14:17], v239 offset:32768
	ds_read_b128 v[130:133], v239 offset:36864
	global_load_lds_dwordx4 v242, s[90:91]
	s_waitcnt lgkmcnt(2)
	v_mfma_f32_32x32x16_bf16 v[82:97], v[166:169], v[150:153], v[82:97]
	v_add_f32_e32 v9, v138, v139
	v_add_f32_e32 v10, v140, v141
	v_add_f32_e32 v9, v9, v10
	v_add_f32_e32 v10, v9, v8
	v_cvt_pk_bf16_f32 v8, v138, v139
	v_cvt_pk_bf16_f32 v9, v140, v141
	v_add_f32_e32 v11, v142, v143
	v_add_f32_e32 v134, v144, v145
	v_mfma_f32_32x32x16_bf16 v[98:113], v[162:165], v[150:153], v[98:113]
	v_add_f32_e32 v11, v11, v134
	v_add_f32_e32 v178, v11, v10
	v_cvt_pk_bf16_f32 v10, v142, v143
	v_cvt_pk_bf16_f32 v11, v144, v145
	ds_read_b128 v[138:141], v240 offset:32768
	ds_read_b128 v[134:137], v240 offset:36864
	s_add_i32 m0, s69, 0x2000
	s_cmp_le_i32 s89, s100
	global_load_lds_dwordx4 v243, s[90:91]
	s_waitcnt lgkmcnt(2)
	v_mfma_f32_32x32x16_bf16 v[82:97], v[14:17], v[154:157], v[82:97]
	v_add_f32_e32 v12, v114, v115
	v_add_f32_e32 v13, v116, v117
	v_add_f32_e32 v12, v12, v13
	v_add_f32_e32 v142, v12, v178
	v_cvt_pk_bf16_f32 v12, v114, v115
	v_cvt_pk_bf16_f32 v13, v116, v117
	v_mfma_f32_32x32x16_bf16 v[98:113], v[130:133], v[154:157], v[98:113]
	v_add_f32_e32 v14, v118, v119
	v_add_f32_e32 v15, v120, v121
	v_add_f32_e32 v14, v14, v15
	v_add_f32_e32 v16, v14, v142
	v_cvt_pk_bf16_f32 v14, v118, v119
	v_cvt_pk_bf16_f32 v15, v120, v121
	s_waitcnt lgkmcnt(0)
	v_mfma_f32_32x32x16_bf16 v[82:97], v[138:141], v[158:161], v[82:97]
	v_add_f32_e32 v17, v122, v123
	v_add_f32_e32 v130, v124, v125
	v_add_f32_e32 v17, v17, v130
	v_add_f32_e32 v16, v17, v16
	v_cvt_pk_bf16_f32 v178, v122, v123
	v_cvt_pk_bf16_f32 v179, v124, v125
	v_add_f32_e32 v17, v126, v127
	v_add_f32_e32 v130, v128, v129
	v_add_f32_e32 v17, v17, v130
	v_add_f32_e32 v16, v17, v16
	v_cvt_pk_bf16_f32 v180, v126, v127
	v_cvt_pk_bf16_f32 v181, v128, v129
	v_mfma_f32_32x32x16_bf16 v[98:113], v[134:137], v[158:161], v[98:113]
	ds_read_b64_tr_b16 v[194:195], v214 offset:32768
	ds_read_b64_tr_b16 v[196:197], v214 offset:33024
	ds_read_b64_tr_b16 v[190:191], v214 offset:36864
	ds_read_b64_tr_b16 v[192:193], v214 offset:37120
	ds_read_b64_tr_b16 v[186:187], v214 offset:40960
	ds_read_b64_tr_b16 v[188:189], v214 offset:41216
	ds_read_b64_tr_b16 v[182:183], v214 offset:45056
	ds_read_b64_tr_b16 v[184:185], v214 offset:45312
	s_cbranch_scc0 .Lp2s_disp2_u2
; template <int VAR> ...
;     ...
;     GAPB(0, pa0); GAPB(1, pa1); GAPB(2, pa2); GAPB(3, pa3); GAPB(4, pa0); GAPB(5, pa1); GAPB(6, pa2); GAPB(7, pa3);
;     GAPB(8, pa0); GAPB(9, pa1); GAPB(10, pa2); GAPB(11, pa3);
;     if (wv == 3) asm volatile("s_waitcnt vmcnt(3)" ::: "memory"); else if (wv == 2) asm volatile("s_waitcnt vmcnt(2)" ::: "memory"); else asm volatile("s_waitcnt vmcnt(0)" ::: "memory");
;     asm volatile("s_waitcnt lgkmcnt(0)\n\ts_barrier" ::: "memory");
;     if (pre) { const char* a0_ = Kn + (((0 + hi) ^ sw) << 4); const char* a1_ = Kn + (((2 + hi) ^ sw) << 4);
;         kp[0] = *reinterpret_cast<const bf16x8*>(a0_); kp[1] = *reinterpret_cast<const bf16x8*>(a0_ + 32 * 128); kp[2] = *reinterpret_cast<const bf16x8*>(a1_); kp[3] = *reinterpret_cast<const bf16x8*>(a1_ + 32 * 128); }
.LBB0_385_u2:
	s_waitcnt lgkmcnt(4)
	v_mfma_f32_32x32x16_bf16 v[66:81], v[4:7], v[194:197], v[66:81]
	v_exp_f32_e32 v82, v82
	v_exp_f32_e32 v98, v98
	ds_read_b64_tr_b16 v[114:115], v214 offset:33280
	ds_read_b64_tr_b16 v[116:117], v214 offset:33536
	v_mfma_f32_32x32x16_bf16 v[66:81], v[8:11], v[190:193], v[66:81]
	v_exp_f32_e32 v83, v83
	v_exp_f32_e32 v99, v99
	ds_read_b64_tr_b16 v[118:119], v214 offset:37376
	ds_read_b64_tr_b16 v[120:121], v214 offset:37632
	s_waitcnt lgkmcnt(4)
	v_mfma_f32_32x32x16_bf16 v[66:81], v[12:15], v[186:189], v[66:81]
	v_exp_f32_e32 v84, v84
	v_exp_f32_e32 v100, v100
	ds_read_b64_tr_b16 v[122:123], v214 offset:41472
	ds_read_b64_tr_b16 v[124:125], v214 offset:41728
	v_mfma_f32_32x32x16_bf16 v[66:81], v[178:181], v[182:185], v[66:81]
	v_exp_f32_e32 v85, v85
	v_exp_f32_e32 v101, v101
	ds_read_b64_tr_b16 v[126:127], v214 offset:45568
	ds_read_b64_tr_b16 v[128:129], v214 offset:45824
	s_waitcnt lgkmcnt(4)
	v_mfma_f32_32x32x16_bf16 v[50:65], v[4:7], v[114:117], v[50:65]
	v_exp_f32_e32 v86, v86
	v_exp_f32_e32 v102, v102
	v_exp_f32_e32 v94, v94
	ds_read_b64_tr_b16 v[130:131], v214 offset:33792
	ds_read_b64_tr_b16 v[132:133], v214 offset:34048
	ds_read_b64_tr_b16 v[114:115], v214 offset:34304
	ds_read_b64_tr_b16 v[116:117], v214 offset:34560
	v_mfma_f32_32x32x16_bf16 v[50:65], v[8:11], v[118:121], v[50:65]
	v_exp_f32_e32 v87, v87
	v_exp_f32_e32 v103, v103
	v_exp_f32_e32 v110, v110
	ds_read_b64_tr_b16 v[134:135], v214 offset:37888
	ds_read_b64_tr_b16 v[136:137], v214 offset:38144
	ds_read_b64_tr_b16 v[118:119], v214 offset:38400
	ds_read_b64_tr_b16 v[120:121], v214 offset:38656
	s_waitcnt lgkmcnt(8)
	v_mfma_f32_32x32x16_bf16 v[50:65], v[12:15], v[122:125], v[50:65]
	v_exp_f32_e32 v88, v88
	v_exp_f32_e32 v104, v104
	v_exp_f32_e32 v95, v95
	ds_read_b64_tr_b16 v[138:139], v214 offset:41984
	ds_read_b64_tr_b16 v[140:141], v214 offset:42240
	ds_read_b64_tr_b16 v[122:123], v214 offset:42496
	ds_read_b64_tr_b16 v[124:125], v214 offset:42752
	v_mfma_f32_32x32x16_bf16 v[50:65], v[178:181], v[126:129], v[50:65]
	v_exp_f32_e32 v89, v89
	v_exp_f32_e32 v105, v105
	v_exp_f32_e32 v111, v111
	ds_read_b64_tr_b16 v[142:143], v214 offset:46080
	ds_read_b64_tr_b16 v[144:145], v214 offset:46336
	ds_read_b64_tr_b16 v[126:127], v214 offset:46592
	ds_read_b64_tr_b16 v[128:129], v214 offset:46848
	s_waitcnt lgkmcnt(10)
	v_mfma_f32_32x32x16_bf16 v[34:49], v[4:7], v[130:133], v[34:49]
	v_exp_f32_e32 v90, v90
	v_exp_f32_e32 v106, v106
	v_exp_f32_e32 v96, v96
	v_mfma_f32_32x32x16_bf16 v[34:49], v[8:11], v[134:137], v[34:49]
	v_exp_f32_e32 v91, v91
	v_exp_f32_e32 v107, v107
	v_exp_f32_e32 v112, v112
	s_waitcnt lgkmcnt(2)
	v_mfma_f32_32x32x16_bf16 v[34:49], v[12:15], v[138:141], v[34:49]
	v_exp_f32_e32 v92, v92
	v_exp_f32_e32 v108, v108
	v_exp_f32_e32 v97, v97
	v_mfma_f32_32x32x16_bf16 v[34:49], v[178:181], v[142:145], v[34:49]
	v_exp_f32_e32 v93, v93
	v_exp_f32_e32 v109, v109
	v_exp_f32_e32 v113, v113
	s_waitcnt vmcnt(3) lgkmcnt(0)
	s_barrier
	s_cmp_gt_i32 s62, s60
	s_cbranch_scc1 .LBB0_394_u2
	ds_read_b128 v[174:177], v237 offset:40960
	ds_read_b128 v[170:173], v237 offset:45056
	ds_read_b128 v[166:169], v238 offset:40960
	ds_read_b128 v[162:165], v238 offset:45056
